# mlaprep item: all 36 loads of a pass issued up front (no reload), V tr_load 16 loads batched
# speedup vs baseline: 1.0394x; 1.0142x over previous
; DI float bflo(unsigned u) { return __uint_as_float(u << 16); }
; DI float bfhi(unsigned u) { return __uint_as_float(u & 0xffff0000u); }
; DI void mlaprep_item(const Params& p, int L, int item, char* smem) {
;     ...
;   for (int which = 0; which < 2; ++which) {
;     const bfu* srcA = which ? (p.kvraw + t * 512 + h * 128) : (p.qraw + t * 384 + h * 96);
;     const bfu* srcB = which ? (p.krope + t * 32) : (p.qraw + t * 384 + h * 96 + 64);
;     const float* g = (which ? p.mla_kn_g : p.mla_qn_g) + L * 96;
;     float ss = 0.f;
; #pragma unroll
;     for (int c = 0; c < 12; ++c) {
;       u32x4 v = *(const u32x4*)((c < 8) ? (srcA + c * 8) : (srcB + (c - 8) * 8));
; #pragma unroll
;       for (int q = 0; q < 4; ++q) { float lo = bflo(v[q]), hi = bfhi(v[q]); ss += lo * lo + hi * hi; }
;     }
.LBB0_198:
	s_nop 0
	v_cndmask_b32_e64 v0, 0, 1, s[6:7]
	v_cmp_ne_u32_e32 vcc, 1, v0
	v_cndmask_b32_e64 v61, v51, v53, s[6:7]
	v_cndmask_b32_e64 v60, v50, v52, s[6:7]
	v_mov_b32_e32 v0, 0x3dd105ec
	v_cndmask_b32_e64 v82, 1.0, v0, s[6:7]
	v_cndmask_b32_e64 v59, v55, v57, s[6:7]
	v_cndmask_b32_e64 v58, v54, v56, s[6:7]
	s_and_b64 s[2:3], s[6:7], exec
	s_cselect_b32 s4, s18, s20
	s_cselect_b32 s2, s58, s24
	s_cselect_b32 s3, s59, s25
	s_cselect_b32 s5, s19, s21
	s_add_u32 s4, s4, s34
	s_addc_u32 s5, s5, s35
	s_mov_b64 s[6:7], 0
	s_and_b64 vcc, exec, vcc
	global_load_dwordx4 v[118:121], v[60:61], off
	global_load_dwordx4 v[122:125], v[60:61], off offset:16
	global_load_dwordx4 v[126:129], v[60:61], off offset:32
	global_load_dwordx4 v[130:133], v[60:61], off offset:48
	global_load_dwordx4 v[134:137], v[60:61], off offset:64
	global_load_dwordx4 v[138:141], v[60:61], off offset:80
	global_load_dwordx4 v[142:145], v[60:61], off offset:96
	global_load_dwordx4 v[146:149], v[60:61], off offset:112
	global_load_dwordx4 v[150:153], v[58:59], off
	global_load_dwordx4 v[154:157], v[58:59], off offset:16
	global_load_dwordx4 v[158:161], v[58:59], off offset:32
	global_load_dwordx4 v[162:165], v[58:59], off offset:48
	global_load_dwordx4 v[62:65], v189, s[4:5]
	global_load_dwordx4 v[66:69], v189, s[4:5] offset:16
	global_load_dwordx4 v[70:73], v189, s[4:5] offset:32
	global_load_dwordx4 v[74:77], v189, s[4:5] offset:48
	global_load_dwordx4 v[78:81], v189, s[4:5] offset:64
	global_load_dwordx4 v[84:87], v189, s[4:5] offset:80
	global_load_dwordx4 v[88:91], v189, s[4:5] offset:96
	global_load_dwordx4 v[92:95], v189, s[4:5] offset:112
	global_load_dwordx4 v[96:99], v189, s[4:5] offset:128
	global_load_dwordx4 v[100:103], v189, s[4:5] offset:144
	global_load_dwordx4 v[104:107], v189, s[4:5] offset:160
	global_load_dwordx4 v[108:111], v189, s[4:5] offset:176
	global_load_dwordx4 v[112:115], v189, s[4:5] offset:192
	global_load_dwordx4 v[166:169], v189, s[4:5] offset:208
	global_load_dwordx4 v[170:173], v189, s[4:5] offset:224
	global_load_dwordx4 v[174:177], v189, s[4:5] offset:240
	global_load_dwordx4 v[178:181], v189, s[4:5] offset:256
	global_load_dwordx4 v[190:193], v189, s[4:5] offset:272
	global_load_dwordx4 v[194:197], v189, s[4:5] offset:288
	global_load_dwordx4 v[198:201], v189, s[4:5] offset:304
	global_load_dwordx4 v[202:205], v189, s[4:5] offset:320
	global_load_dwordx4 v[206:209], v189, s[4:5] offset:336
	global_load_dwordx4 v[240:243], v189, s[4:5] offset:352
	global_load_dwordx4 v[244:247], v189, s[4:5] offset:368
	v_lshl_add_u64 v[10:11], s[2:3], 0, v[16:17]
	s_waitcnt vmcnt(24)
	v_lshlrev_b32_e32 v4, 16, v118
	v_and_b32_e32 v5, 0xffff0000, v118
	v_mul_f32_e32 v0, v4, v4
	v_fmac_f32_e32 v0, v5, v5
	v_lshlrev_b32_e32 v6, 16, v119
	v_and_b32_e32 v7, 0xffff0000, v119
	v_mul_f32_e32 v1, v6, v6
	v_fmac_f32_e32 v1, v7, v7
	v_lshlrev_b32_e32 v4, 16, v120
	v_and_b32_e32 v5, 0xffff0000, v120
	v_mul_f32_e32 v2, v4, v4
	v_fmac_f32_e32 v2, v5, v5
	v_lshlrev_b32_e32 v6, 16, v121
	v_and_b32_e32 v7, 0xffff0000, v121
	v_mul_f32_e32 v3, v6, v6
	v_fmac_f32_e32 v3, v7, v7
	v_lshlrev_b32_e32 v4, 16, v122
	v_and_b32_e32 v5, 0xffff0000, v122
	v_fmac_f32_e32 v0, v4, v4
	v_fmac_f32_e32 v0, v5, v5
	v_lshlrev_b32_e32 v6, 16, v123
	v_and_b32_e32 v7, 0xffff0000, v123
	v_fmac_f32_e32 v1, v6, v6
	v_fmac_f32_e32 v1, v7, v7
	v_lshlrev_b32_e32 v4, 16, v124
	v_and_b32_e32 v5, 0xffff0000, v124
	v_fmac_f32_e32 v2, v4, v4
	v_fmac_f32_e32 v2, v5, v5
	v_lshlrev_b32_e32 v6, 16, v125
	v_and_b32_e32 v7, 0xffff0000, v125
	v_fmac_f32_e32 v3, v6, v6
	v_fmac_f32_e32 v3, v7, v7
	v_lshlrev_b32_e32 v4, 16, v126
	v_and_b32_e32 v5, 0xffff0000, v126
	v_fmac_f32_e32 v0, v4, v4
	v_fmac_f32_e32 v0, v5, v5
	v_lshlrev_b32_e32 v6, 16, v127
	v_and_b32_e32 v7, 0xffff0000, v127
	v_fmac_f32_e32 v1, v6, v6
	v_fmac_f32_e32 v1, v7, v7
	v_lshlrev_b32_e32 v4, 16, v128
	v_and_b32_e32 v5, 0xffff0000, v128
	v_fmac_f32_e32 v2, v4, v4
	v_fmac_f32_e32 v2, v5, v5
	v_lshlrev_b32_e32 v6, 16, v129
	v_and_b32_e32 v7, 0xffff0000, v129
	v_fmac_f32_e32 v3, v6, v6
	v_fmac_f32_e32 v3, v7, v7
	v_lshlrev_b32_e32 v4, 16, v130
	v_and_b32_e32 v5, 0xffff0000, v130
	v_fmac_f32_e32 v0, v4, v4
	v_fmac_f32_e32 v0, v5, v5
	v_lshlrev_b32_e32 v6, 16, v131
	v_and_b32_e32 v7, 0xffff0000, v131
	v_fmac_f32_e32 v1, v6, v6
	v_fmac_f32_e32 v1, v7, v7
	v_lshlrev_b32_e32 v4, 16, v132
	v_and_b32_e32 v5, 0xffff0000, v132
	v_fmac_f32_e32 v2, v4, v4
	v_fmac_f32_e32 v2, v5, v5
	v_lshlrev_b32_e32 v6, 16, v133
	v_and_b32_e32 v7, 0xffff0000, v133
	v_fmac_f32_e32 v3, v6, v6
	v_fmac_f32_e32 v3, v7, v7
	v_lshlrev_b32_e32 v4, 16, v134
	v_and_b32_e32 v5, 0xffff0000, v134
	v_fmac_f32_e32 v0, v4, v4
	v_fmac_f32_e32 v0, v5, v5
	v_lshlrev_b32_e32 v6, 16, v135
	v_and_b32_e32 v7, 0xffff0000, v135
	v_fmac_f32_e32 v1, v6, v6
	v_fmac_f32_e32 v1, v7, v7
	v_lshlrev_b32_e32 v4, 16, v136
	v_and_b32_e32 v5, 0xffff0000, v136
	v_fmac_f32_e32 v2, v4, v4
	v_fmac_f32_e32 v2, v5, v5
	v_lshlrev_b32_e32 v6, 16, v137
	v_and_b32_e32 v7, 0xffff0000, v137
	v_fmac_f32_e32 v3, v6, v6
	v_fmac_f32_e32 v3, v7, v7
	v_lshlrev_b32_e32 v4, 16, v138
	v_and_b32_e32 v5, 0xffff0000, v138
	v_fmac_f32_e32 v0, v4, v4
	v_fmac_f32_e32 v0, v5, v5
	v_lshlrev_b32_e32 v6, 16, v139
	v_and_b32_e32 v7, 0xffff0000, v139
	v_fmac_f32_e32 v1, v6, v6
	v_fmac_f32_e32 v1, v7, v7
	v_lshlrev_b32_e32 v4, 16, v140
	v_and_b32_e32 v5, 0xffff0000, v140
	v_fmac_f32_e32 v2, v4, v4
	v_fmac_f32_e32 v2, v5, v5
	v_lshlrev_b32_e32 v6, 16, v141
	v_and_b32_e32 v7, 0xffff0000, v141
	v_fmac_f32_e32 v3, v6, v6
	v_fmac_f32_e32 v3, v7, v7
	v_lshlrev_b32_e32 v4, 16, v142
	v_and_b32_e32 v5, 0xffff0000, v142
	v_fmac_f32_e32 v0, v4, v4
; DI unsigned pk2(float a, float b) { f32x2_t v = {a, b}; bf16x2_t r_ = __builtin_convertvector(v, bf16x2_t); return __builtin_bit_cast(unsigned, r_); }
; DI float bflo(unsigned u) { return __uint_as_float(u << 16); }
; DI float bfhi(unsigned u) { return __uint_as_float(u & 0xffff0000u); }
; DI void mlaprep_item(const Params& p, int L, int item, char* smem) {
;     ...
;     const float sc = which ? 1.f : 0.10206207261596577f;
;     const float rs = rsqrtf(ss * (1.f / 96.f) + EPS) * sc;
;     bfu* dst = (which ? p.k_mla : p.q_mla) + (((size_t)(b * 4 + h)) * S + spos) * 96;
; #pragma unroll
;     for (int c = 0; c < 8; ++c) {
;       u32x4 v = *(const u32x4*)(srcA + c * 8);
;       const float* gc = g + c * 8;
;       *(u32x4*)(dst + c * 8) = (u32x4){pk2(bflo(v[0]) * rs * gc[0], bfhi(v[0]) * rs * gc[1]), pk2(bflo(v[1]) * rs * gc[2], bfhi(v[1]) * rs * gc[3]),
;                                        pk2(bflo(v[2]) * rs * gc[4], bfhi(v[2]) * rs * gc[5]), pk2(bflo(v[3]) * rs * gc[6], bfhi(v[3]) * rs * gc[7])};
;     }
	v_fmac_f32_e32 v0, v5, v5
	v_lshlrev_b32_e32 v6, 16, v143
	v_and_b32_e32 v7, 0xffff0000, v143
	v_fmac_f32_e32 v1, v6, v6
	v_fmac_f32_e32 v1, v7, v7
	v_lshlrev_b32_e32 v4, 16, v144
	v_and_b32_e32 v5, 0xffff0000, v144
	v_fmac_f32_e32 v2, v4, v4
	v_fmac_f32_e32 v2, v5, v5
	v_lshlrev_b32_e32 v6, 16, v145
	v_and_b32_e32 v7, 0xffff0000, v145
	v_fmac_f32_e32 v3, v6, v6
	v_fmac_f32_e32 v3, v7, v7
	v_lshlrev_b32_e32 v4, 16, v146
	v_and_b32_e32 v5, 0xffff0000, v146
	v_fmac_f32_e32 v0, v4, v4
	v_fmac_f32_e32 v0, v5, v5
	v_lshlrev_b32_e32 v6, 16, v147
	v_and_b32_e32 v7, 0xffff0000, v147
	v_fmac_f32_e32 v1, v6, v6
	v_fmac_f32_e32 v1, v7, v7
	v_lshlrev_b32_e32 v4, 16, v148
	v_and_b32_e32 v5, 0xffff0000, v148
	v_fmac_f32_e32 v2, v4, v4
	v_fmac_f32_e32 v2, v5, v5
	v_lshlrev_b32_e32 v6, 16, v149
	v_and_b32_e32 v7, 0xffff0000, v149
	v_fmac_f32_e32 v3, v6, v6
	v_fmac_f32_e32 v3, v7, v7
	v_lshlrev_b32_e32 v4, 16, v150
	v_and_b32_e32 v5, 0xffff0000, v150
	v_fmac_f32_e32 v0, v4, v4
	v_fmac_f32_e32 v0, v5, v5
	v_lshlrev_b32_e32 v6, 16, v151
	v_and_b32_e32 v7, 0xffff0000, v151
	v_fmac_f32_e32 v1, v6, v6
	v_fmac_f32_e32 v1, v7, v7
	v_lshlrev_b32_e32 v4, 16, v152
	v_and_b32_e32 v5, 0xffff0000, v152
	v_fmac_f32_e32 v2, v4, v4
	v_fmac_f32_e32 v2, v5, v5
	v_lshlrev_b32_e32 v6, 16, v153
	v_and_b32_e32 v7, 0xffff0000, v153
	v_fmac_f32_e32 v3, v6, v6
	v_fmac_f32_e32 v3, v7, v7
	v_lshlrev_b32_e32 v4, 16, v154
	v_and_b32_e32 v5, 0xffff0000, v154
	v_fmac_f32_e32 v0, v4, v4
	v_fmac_f32_e32 v0, v5, v5
	v_lshlrev_b32_e32 v6, 16, v155
	v_and_b32_e32 v7, 0xffff0000, v155
	v_fmac_f32_e32 v1, v6, v6
	v_fmac_f32_e32 v1, v7, v7
	v_lshlrev_b32_e32 v4, 16, v156
	v_and_b32_e32 v5, 0xffff0000, v156
	v_fmac_f32_e32 v2, v4, v4
	v_fmac_f32_e32 v2, v5, v5
	v_lshlrev_b32_e32 v6, 16, v157
	v_and_b32_e32 v7, 0xffff0000, v157
	v_fmac_f32_e32 v3, v6, v6
	v_fmac_f32_e32 v3, v7, v7
	v_lshlrev_b32_e32 v4, 16, v158
	v_and_b32_e32 v5, 0xffff0000, v158
	v_fmac_f32_e32 v0, v4, v4
	v_fmac_f32_e32 v0, v5, v5
	v_lshlrev_b32_e32 v6, 16, v159
	v_and_b32_e32 v7, 0xffff0000, v159
	v_fmac_f32_e32 v1, v6, v6
	v_fmac_f32_e32 v1, v7, v7
	v_lshlrev_b32_e32 v4, 16, v160
	v_and_b32_e32 v5, 0xffff0000, v160
	v_fmac_f32_e32 v2, v4, v4
	v_fmac_f32_e32 v2, v5, v5
	v_lshlrev_b32_e32 v6, 16, v161
	v_and_b32_e32 v7, 0xffff0000, v161
	v_fmac_f32_e32 v3, v6, v6
	v_fmac_f32_e32 v3, v7, v7
	v_lshlrev_b32_e32 v4, 16, v162
	v_and_b32_e32 v5, 0xffff0000, v162
	v_fmac_f32_e32 v0, v4, v4
	v_fmac_f32_e32 v0, v5, v5
	v_lshlrev_b32_e32 v6, 16, v163
	v_and_b32_e32 v7, 0xffff0000, v163
	v_fmac_f32_e32 v1, v6, v6
	v_fmac_f32_e32 v1, v7, v7
	v_lshlrev_b32_e32 v4, 16, v164
	v_and_b32_e32 v5, 0xffff0000, v164
	v_fmac_f32_e32 v2, v4, v4
	v_fmac_f32_e32 v2, v5, v5
	v_lshlrev_b32_e32 v6, 16, v165
	v_and_b32_e32 v7, 0xffff0000, v165
	v_fmac_f32_e32 v3, v6, v6
	v_fmac_f32_e32 v3, v7, v7
	v_add_f32_e32 v0, v0, v1
	v_add_f32_e32 v2, v2, v3
	v_add_f32_e32 v0, v0, v2
	v_fmamk_f32 v0, v0, 0x3c2aaaab, v225
	s_nop 0
	v_cmp_gt_f32_e64 s[2:3], s10, v0
	v_mul_f32_e32 v1, 0x4b800000, v0
	s_nop 0
	v_cndmask_b32_e64 v0, v0, v1, s[2:3]
	v_rsq_f32_e32 v0, v0
	s_nop 0
	v_mul_f32_e32 v1, 0x45800000, v0
	v_cndmask_b32_e64 v0, v0, v1, s[2:3]
	v_mul_f32_e32 v12, v82, v0
	s_waitcnt vmcnt(0)
	v_lshlrev_b32_e32 v0, 16, v118
	v_and_b32_e32 v1, 0xffff0000, v118
	v_lshlrev_b32_e32 v2, 16, v119
	v_and_b32_e32 v3, 0xffff0000, v119
	v_lshlrev_b32_e32 v4, 16, v120
	v_and_b32_e32 v5, 0xffff0000, v120
	v_lshlrev_b32_e32 v14, 16, v121
	v_and_b32_e32 v15, 0xffff0000, v121
	v_pk_mul_f32 v[0:1], v[12:13], v[0:1] op_sel_hi:[0,1]
	v_pk_mul_f32 v[2:3], v[12:13], v[2:3] op_sel_hi:[0,1]
	v_pk_mul_f32 v[4:5], v[12:13], v[4:5] op_sel_hi:[0,1]
	v_pk_mul_f32 v[14:15], v[12:13], v[14:15] op_sel_hi:[0,1]
	v_pk_mul_f32 v[0:1], v[62:63], v[0:1]
	v_pk_mul_f32 v[2:3], v[64:65], v[2:3]
	v_pk_mul_f32 v[4:5], v[66:67], v[4:5]
	v_pk_mul_f32 v[14:15], v[68:69], v[14:15]
	s_nop 0
	v_cvt_pk_bf16_f32 v6, v0, v1
	v_cvt_pk_bf16_f32 v7, v2, v3
	v_cvt_pk_bf16_f32 v8, v4, v5
	v_cvt_pk_bf16_f32 v9, v14, v15
	global_store_dwordx4 v[10:11], v[6:9], off
	v_lshlrev_b32_e32 v0, 16, v122
	v_and_b32_e32 v1, 0xffff0000, v122
	v_lshlrev_b32_e32 v2, 16, v123
	v_and_b32_e32 v3, 0xffff0000, v123
	v_lshlrev_b32_e32 v4, 16, v124
	v_and_b32_e32 v5, 0xffff0000, v124
	v_lshlrev_b32_e32 v14, 16, v125
	v_and_b32_e32 v15, 0xffff0000, v125
	v_pk_mul_f32 v[0:1], v[12:13], v[0:1] op_sel_hi:[0,1]
	v_pk_mul_f32 v[2:3], v[12:13], v[2:3] op_sel_hi:[0,1]
	v_pk_mul_f32 v[4:5], v[12:13], v[4:5] op_sel_hi:[0,1]
	v_pk_mul_f32 v[14:15], v[12:13], v[14:15] op_sel_hi:[0,1]
	v_pk_mul_f32 v[0:1], v[70:71], v[0:1]
	v_pk_mul_f32 v[2:3], v[72:73], v[2:3]
	v_pk_mul_f32 v[4:5], v[74:75], v[4:5]
	v_pk_mul_f32 v[14:15], v[76:77], v[14:15]
	s_nop 0
	v_cvt_pk_bf16_f32 v6, v0, v1
	v_cvt_pk_bf16_f32 v7, v2, v3
	v_cvt_pk_bf16_f32 v8, v4, v5
	v_cvt_pk_bf16_f32 v9, v14, v15
	global_store_dwordx4 v[10:11], v[6:9], off offset:16
	v_lshlrev_b32_e32 v0, 16, v126
	v_and_b32_e32 v1, 0xffff0000, v126
	v_lshlrev_b32_e32 v2, 16, v127
	v_and_b32_e32 v3, 0xffff0000, v127
	v_lshlrev_b32_e32 v4, 16, v128
	v_and_b32_e32 v5, 0xffff0000, v128
	v_lshlrev_b32_e32 v14, 16, v129
	v_and_b32_e32 v15, 0xffff0000, v129
	v_pk_mul_f32 v[0:1], v[12:13], v[0:1] op_sel_hi:[0,1]
	v_pk_mul_f32 v[2:3], v[12:13], v[2:3] op_sel_hi:[0,1]
	v_pk_mul_f32 v[4:5], v[12:13], v[4:5] op_sel_hi:[0,1]
	v_pk_mul_f32 v[14:15], v[12:13], v[14:15] op_sel_hi:[0,1]
	v_pk_mul_f32 v[0:1], v[78:79], v[0:1]
	v_pk_mul_f32 v[2:3], v[80:81], v[2:3]
	v_pk_mul_f32 v[4:5], v[84:85], v[4:5]
	v_pk_mul_f32 v[14:15], v[86:87], v[14:15]
	s_nop 0
	v_cvt_pk_bf16_f32 v6, v0, v1
	v_cvt_pk_bf16_f32 v7, v2, v3
; DI unsigned pk2(float a, float b) { f32x2_t v = {a, b}; bf16x2_t r_ = __builtin_convertvector(v, bf16x2_t); return __builtin_bit_cast(unsigned, r_); }
; DI float bflo(unsigned u) { return __uint_as_float(u << 16); }
; DI float bfhi(unsigned u) { return __uint_as_float(u & 0xffff0000u); }
; DI void mlaprep_item(const Params& p, int L, int item, char* smem) {
;     ...
;     for (int c = 0; c < 8; ++c) {
;       u32x4 v = *(const u32x4*)(srcA + c * 8);
;       const float* gc = g + c * 8;
;       *(u32x4*)(dst + c * 8) = (u32x4){pk2(bflo(v[0]) * rs * gc[0], bfhi(v[0]) * rs * gc[1]), pk2(bflo(v[1]) * rs * gc[2], bfhi(v[1]) * rs * gc[3]),
;                                        pk2(bflo(v[2]) * rs * gc[4], bfhi(v[2]) * rs * gc[5]), pk2(bflo(v[3]) * rs * gc[6], bfhi(v[3]) * rs * gc[7])};
;     }
; #pragma unroll
;     for (int c = 0; c < 2; ++c) {
;       u32x4 va = *(const u32x4*)(srcB + c * 8);
;       u32x4 vb = *(const u32x4*)(srcB + 16 + c * 8);
;       float oa[8], ob[8];
; #pragma unroll
;       for (int q = 0; q < 8; ++q) {
;         const int i2 = c * 8 + q;
;         float a = ((q & 1) ? bfhi(va[q >> 1]) : bflo(va[q >> 1])) * rs * g[64 + i2];
;         float bb = ((q & 1) ? bfhi(vb[q >> 1]) : bflo(vb[q >> 1])) * rs * g[80 + i2];
;         float inv = expf(-9.210340371976184f * (float)i2 / 16.f);
;         float ang = (float)spos * inv;
;         double rv = (double)ang * 0.15915494309189535; rv -= floor(rv);
;         float fr = (float)rv;
;         float cs = __builtin_amdgcn_cosf(fr), sn = __builtin_amdgcn_sinf(fr);
;         oa[q] = a * cs - bb * sn; ob[q] = bb * cs + a * sn;
;       }
;       *(u32x4*)(dst + 64 + c * 8) = (u32x4){pk2(oa[0], oa[1]), pk2(oa[2], oa[3]), pk2(oa[4], oa[5]), pk2(oa[6], oa[7])};
;       *(u32x4*)(dst + 80 + c * 8) = (u32x4){pk2(ob[0], ob[1]), pk2(ob[2], ob[3]), pk2(ob[4], ob[5]), pk2(ob[6], ob[7])};
	v_cvt_pk_bf16_f32 v8, v4, v5
	v_cvt_pk_bf16_f32 v9, v14, v15
	global_store_dwordx4 v[10:11], v[6:9], off offset:32
	v_lshlrev_b32_e32 v0, 16, v130
	v_and_b32_e32 v1, 0xffff0000, v130
	v_lshlrev_b32_e32 v2, 16, v131
	v_and_b32_e32 v3, 0xffff0000, v131
	v_lshlrev_b32_e32 v4, 16, v132
	v_and_b32_e32 v5, 0xffff0000, v132
	v_lshlrev_b32_e32 v14, 16, v133
	v_and_b32_e32 v15, 0xffff0000, v133
	v_pk_mul_f32 v[0:1], v[12:13], v[0:1] op_sel_hi:[0,1]
	v_pk_mul_f32 v[2:3], v[12:13], v[2:3] op_sel_hi:[0,1]
	v_pk_mul_f32 v[4:5], v[12:13], v[4:5] op_sel_hi:[0,1]
	v_pk_mul_f32 v[14:15], v[12:13], v[14:15] op_sel_hi:[0,1]
	v_pk_mul_f32 v[0:1], v[88:89], v[0:1]
	v_pk_mul_f32 v[2:3], v[90:91], v[2:3]
	v_pk_mul_f32 v[4:5], v[92:93], v[4:5]
	v_pk_mul_f32 v[14:15], v[94:95], v[14:15]
	s_nop 0
	v_cvt_pk_bf16_f32 v6, v0, v1
	v_cvt_pk_bf16_f32 v7, v2, v3
	v_cvt_pk_bf16_f32 v8, v4, v5
	v_cvt_pk_bf16_f32 v9, v14, v15
	global_store_dwordx4 v[10:11], v[6:9], off offset:48
	v_lshlrev_b32_e32 v0, 16, v134
	v_and_b32_e32 v1, 0xffff0000, v134
	v_lshlrev_b32_e32 v2, 16, v135
	v_and_b32_e32 v3, 0xffff0000, v135
	v_lshlrev_b32_e32 v4, 16, v136
	v_and_b32_e32 v5, 0xffff0000, v136
	v_lshlrev_b32_e32 v14, 16, v137
	v_and_b32_e32 v15, 0xffff0000, v137
	v_pk_mul_f32 v[0:1], v[12:13], v[0:1] op_sel_hi:[0,1]
	v_pk_mul_f32 v[2:3], v[12:13], v[2:3] op_sel_hi:[0,1]
	v_pk_mul_f32 v[4:5], v[12:13], v[4:5] op_sel_hi:[0,1]
	v_pk_mul_f32 v[14:15], v[12:13], v[14:15] op_sel_hi:[0,1]
	v_pk_mul_f32 v[0:1], v[96:97], v[0:1]
	v_pk_mul_f32 v[2:3], v[98:99], v[2:3]
	v_pk_mul_f32 v[4:5], v[100:101], v[4:5]
	v_pk_mul_f32 v[14:15], v[102:103], v[14:15]
	s_nop 0
	v_cvt_pk_bf16_f32 v6, v0, v1
	v_cvt_pk_bf16_f32 v7, v2, v3
	v_cvt_pk_bf16_f32 v8, v4, v5
	v_cvt_pk_bf16_f32 v9, v14, v15
	global_store_dwordx4 v[10:11], v[6:9], off offset:64
	v_lshlrev_b32_e32 v0, 16, v138
	v_and_b32_e32 v1, 0xffff0000, v138
	v_lshlrev_b32_e32 v2, 16, v139
	v_and_b32_e32 v3, 0xffff0000, v139
	v_lshlrev_b32_e32 v4, 16, v140
	v_and_b32_e32 v5, 0xffff0000, v140
	v_lshlrev_b32_e32 v14, 16, v141
	v_and_b32_e32 v15, 0xffff0000, v141
	v_pk_mul_f32 v[0:1], v[12:13], v[0:1] op_sel_hi:[0,1]
	v_pk_mul_f32 v[2:3], v[12:13], v[2:3] op_sel_hi:[0,1]
	v_pk_mul_f32 v[4:5], v[12:13], v[4:5] op_sel_hi:[0,1]
	v_pk_mul_f32 v[14:15], v[12:13], v[14:15] op_sel_hi:[0,1]
	v_pk_mul_f32 v[0:1], v[104:105], v[0:1]
	v_pk_mul_f32 v[2:3], v[106:107], v[2:3]
	v_pk_mul_f32 v[4:5], v[108:109], v[4:5]
	v_pk_mul_f32 v[14:15], v[110:111], v[14:15]
	s_nop 0
	v_cvt_pk_bf16_f32 v6, v0, v1
	v_cvt_pk_bf16_f32 v7, v2, v3
	v_cvt_pk_bf16_f32 v8, v4, v5
	v_cvt_pk_bf16_f32 v9, v14, v15
	global_store_dwordx4 v[10:11], v[6:9], off offset:80
	v_lshlrev_b32_e32 v0, 16, v142
	v_and_b32_e32 v1, 0xffff0000, v142
	v_lshlrev_b32_e32 v2, 16, v143
	v_and_b32_e32 v3, 0xffff0000, v143
	v_lshlrev_b32_e32 v4, 16, v144
	v_and_b32_e32 v5, 0xffff0000, v144
	v_lshlrev_b32_e32 v14, 16, v145
	v_and_b32_e32 v15, 0xffff0000, v145
	v_pk_mul_f32 v[0:1], v[12:13], v[0:1] op_sel_hi:[0,1]
	v_pk_mul_f32 v[2:3], v[12:13], v[2:3] op_sel_hi:[0,1]
	v_pk_mul_f32 v[4:5], v[12:13], v[4:5] op_sel_hi:[0,1]
	v_pk_mul_f32 v[14:15], v[12:13], v[14:15] op_sel_hi:[0,1]
	v_pk_mul_f32 v[0:1], v[112:113], v[0:1]
	v_pk_mul_f32 v[2:3], v[114:115], v[2:3]
	v_pk_mul_f32 v[4:5], v[166:167], v[4:5]
	v_pk_mul_f32 v[14:15], v[168:169], v[14:15]
	s_nop 0
	v_cvt_pk_bf16_f32 v6, v0, v1
	v_cvt_pk_bf16_f32 v7, v2, v3
	v_cvt_pk_bf16_f32 v8, v4, v5
	v_cvt_pk_bf16_f32 v9, v14, v15
	global_store_dwordx4 v[10:11], v[6:9], off offset:96
	v_lshlrev_b32_e32 v0, 16, v146
	v_and_b32_e32 v1, 0xffff0000, v146
	v_lshlrev_b32_e32 v2, 16, v147
	v_and_b32_e32 v3, 0xffff0000, v147
	v_lshlrev_b32_e32 v4, 16, v148
	v_and_b32_e32 v5, 0xffff0000, v148
	v_lshlrev_b32_e32 v14, 16, v149
	v_and_b32_e32 v15, 0xffff0000, v149
	v_pk_mul_f32 v[0:1], v[12:13], v[0:1] op_sel_hi:[0,1]
	v_pk_mul_f32 v[2:3], v[12:13], v[2:3] op_sel_hi:[0,1]
	v_pk_mul_f32 v[4:5], v[12:13], v[4:5] op_sel_hi:[0,1]
	v_pk_mul_f32 v[14:15], v[12:13], v[14:15] op_sel_hi:[0,1]
	v_pk_mul_f32 v[0:1], v[170:171], v[0:1]
	v_pk_mul_f32 v[2:3], v[172:173], v[2:3]
	v_pk_mul_f32 v[4:5], v[174:175], v[4:5]
	v_pk_mul_f32 v[14:15], v[176:177], v[14:15]
	s_nop 0
	v_cvt_pk_bf16_f32 v6, v0, v1
	v_cvt_pk_bf16_f32 v7, v2, v3
	v_cvt_pk_bf16_f32 v8, v4, v5
	v_cvt_pk_bf16_f32 v9, v14, v15
	global_store_dwordx4 v[10:11], v[6:9], off offset:112
	v_lshlrev_b32_e32 v0, 16, v150
	v_and_b32_e32 v1, 0xffff0000, v150
	v_lshlrev_b32_e32 v2, 16, v158
	v_and_b32_e32 v3, 0xffff0000, v158
	v_pk_mul_f32 v[0:1], v[12:13], v[0:1] op_sel_hi:[0,1]
	v_pk_mul_f32 v[2:3], v[12:13], v[2:3] op_sel_hi:[0,1]
	v_pk_mul_f32 v[0:1], v[0:1], v[178:179]
	v_pk_mul_f32 v[2:3], v[2:3], v[202:203]
	v_pk_mul_f32 v[4:5], v[18:19], v[2:3]
	v_pk_mul_f32 v[14:15], v[20:21], v[2:3]
	v_pk_fma_f32 v[4:5], v[20:21], v[0:1], v[4:5]
	v_pk_fma_f32 v[14:15], v[18:19], v[0:1], v[14:15] neg_lo:[0,0,1] neg_hi:[0,0,1]
	s_nop 0
	v_cvt_pk_bf16_f32 v248, v4, v5
	v_cvt_pk_bf16_f32 v6, v14, v15
	v_lshlrev_b32_e32 v0, 16, v151
	v_and_b32_e32 v1, 0xffff0000, v151
	v_lshlrev_b32_e32 v2, 16, v159
	v_and_b32_e32 v3, 0xffff0000, v159
	v_pk_mul_f32 v[0:1], v[12:13], v[0:1] op_sel_hi:[0,1]
	v_pk_mul_f32 v[2:3], v[12:13], v[2:3] op_sel_hi:[0,1]
	v_pk_mul_f32 v[0:1], v[0:1], v[180:181]
	v_pk_mul_f32 v[2:3], v[2:3], v[204:205]
	v_pk_mul_f32 v[4:5], v[22:23], v[2:3]
	v_pk_mul_f32 v[14:15], v[24:25], v[2:3]
	v_pk_fma_f32 v[4:5], v[24:25], v[0:1], v[4:5]
	v_pk_fma_f32 v[14:15], v[22:23], v[0:1], v[14:15] neg_lo:[0,0,1] neg_hi:[0,0,1]
	s_nop 0
	v_cvt_pk_bf16_f32 v249, v4, v5
	v_cvt_pk_bf16_f32 v7, v14, v15
	v_lshlrev_b32_e32 v0, 16, v152
	v_and_b32_e32 v1, 0xffff0000, v152
; DI unsigned pk2(float a, float b) { f32x2_t v = {a, b}; bf16x2_t r_ = __builtin_convertvector(v, bf16x2_t); return __builtin_bit_cast(unsigned, r_); }
; DI float bflo(unsigned u) { return __uint_as_float(u << 16); }
; DI float bfhi(unsigned u) { return __uint_as_float(u & 0xffff0000u); }
; DI void mlaprep_item(const Params& p, int L, int item, char* smem) {
;     ...
;     for (int c = 0; c < 2; ++c) {
;       u32x4 va = *(const u32x4*)(srcB + c * 8);
;       u32x4 vb = *(const u32x4*)(srcB + 16 + c * 8);
;       float oa[8], ob[8];
; #pragma unroll
;       for (int q = 0; q < 8; ++q) {
;         const int i2 = c * 8 + q;
;         float a = ((q & 1) ? bfhi(va[q >> 1]) : bflo(va[q >> 1])) * rs * g[64 + i2];
;         float bb = ((q & 1) ? bfhi(vb[q >> 1]) : bflo(vb[q >> 1])) * rs * g[80 + i2];
;         float inv = expf(-9.210340371976184f * (float)i2 / 16.f);
;         float ang = (float)spos * inv;
;         double rv = (double)ang * 0.15915494309189535; rv -= floor(rv);
;         float fr = (float)rv;
;         float cs = __builtin_amdgcn_cosf(fr), sn = __builtin_amdgcn_sinf(fr);
;         oa[q] = a * cs - bb * sn; ob[q] = bb * cs + a * sn;
;       }
;       *(u32x4*)(dst + 64 + c * 8) = (u32x4){pk2(oa[0], oa[1]), pk2(oa[2], oa[3]), pk2(oa[4], oa[5]), pk2(oa[6], oa[7])};
;       *(u32x4*)(dst + 80 + c * 8) = (u32x4){pk2(ob[0], ob[1]), pk2(ob[2], ob[3]), pk2(ob[4], ob[5]), pk2(ob[6], ob[7])};
;     }
;   }
;   bfu* T = (bfu*)smem;
;   __syncthreads();
	v_lshlrev_b32_e32 v2, 16, v160
	v_and_b32_e32 v3, 0xffff0000, v160
	v_pk_mul_f32 v[0:1], v[12:13], v[0:1] op_sel_hi:[0,1]
	v_pk_mul_f32 v[2:3], v[12:13], v[2:3] op_sel_hi:[0,1]
	v_pk_mul_f32 v[0:1], v[0:1], v[190:191]
	v_pk_mul_f32 v[2:3], v[2:3], v[206:207]
	v_pk_mul_f32 v[4:5], v[26:27], v[2:3]
	v_pk_mul_f32 v[14:15], v[28:29], v[2:3]
	v_pk_fma_f32 v[4:5], v[28:29], v[0:1], v[4:5]
	v_pk_fma_f32 v[14:15], v[26:27], v[0:1], v[14:15] neg_lo:[0,0,1] neg_hi:[0,0,1]
	s_nop 0
	v_cvt_pk_bf16_f32 v250, v4, v5
	v_cvt_pk_bf16_f32 v8, v14, v15
	v_lshlrev_b32_e32 v0, 16, v153
	v_and_b32_e32 v1, 0xffff0000, v153
	v_lshlrev_b32_e32 v2, 16, v161
	v_and_b32_e32 v3, 0xffff0000, v161
	v_pk_mul_f32 v[0:1], v[12:13], v[0:1] op_sel_hi:[0,1]
	v_pk_mul_f32 v[2:3], v[12:13], v[2:3] op_sel_hi:[0,1]
	v_pk_mul_f32 v[0:1], v[0:1], v[192:193]
	v_pk_mul_f32 v[2:3], v[2:3], v[208:209]
	v_pk_mul_f32 v[4:5], v[30:31], v[2:3]
	v_pk_mul_f32 v[14:15], v[32:33], v[2:3]
	v_pk_fma_f32 v[4:5], v[32:33], v[0:1], v[4:5]
	v_pk_fma_f32 v[14:15], v[30:31], v[0:1], v[14:15] neg_lo:[0,0,1] neg_hi:[0,0,1]
	s_nop 0
	v_cvt_pk_bf16_f32 v251, v4, v5
	v_cvt_pk_bf16_f32 v9, v14, v15
	global_store_dwordx4 v[10:11], v[6:9], off offset:128
	global_store_dwordx4 v[10:11], v[248:251], off offset:160
	v_lshlrev_b32_e32 v0, 16, v154
	v_and_b32_e32 v1, 0xffff0000, v154
	v_lshlrev_b32_e32 v2, 16, v162
	v_and_b32_e32 v3, 0xffff0000, v162
	v_pk_mul_f32 v[0:1], v[12:13], v[0:1] op_sel_hi:[0,1]
	v_pk_mul_f32 v[2:3], v[12:13], v[2:3] op_sel_hi:[0,1]
	v_pk_mul_f32 v[0:1], v[0:1], v[194:195]
	v_pk_mul_f32 v[2:3], v[2:3], v[240:241]
	v_pk_mul_f32 v[4:5], v[34:35], v[2:3]
	v_pk_mul_f32 v[14:15], v[36:37], v[2:3]
	v_pk_fma_f32 v[4:5], v[36:37], v[0:1], v[4:5]
	v_pk_fma_f32 v[14:15], v[34:35], v[0:1], v[14:15] neg_lo:[0,0,1] neg_hi:[0,0,1]
	s_nop 0
	v_cvt_pk_bf16_f32 v248, v4, v5
	v_cvt_pk_bf16_f32 v6, v14, v15
	v_lshlrev_b32_e32 v0, 16, v155
	v_and_b32_e32 v1, 0xffff0000, v155
	v_lshlrev_b32_e32 v2, 16, v163
	v_and_b32_e32 v3, 0xffff0000, v163
	v_pk_mul_f32 v[0:1], v[12:13], v[0:1] op_sel_hi:[0,1]
	v_pk_mul_f32 v[2:3], v[12:13], v[2:3] op_sel_hi:[0,1]
	v_pk_mul_f32 v[0:1], v[0:1], v[196:197]
	v_pk_mul_f32 v[2:3], v[2:3], v[242:243]
	v_pk_mul_f32 v[4:5], v[38:39], v[2:3]
	v_pk_mul_f32 v[14:15], v[40:41], v[2:3]
	v_pk_fma_f32 v[4:5], v[40:41], v[0:1], v[4:5]
	v_pk_fma_f32 v[14:15], v[38:39], v[0:1], v[14:15] neg_lo:[0,0,1] neg_hi:[0,0,1]
	s_nop 0
	v_cvt_pk_bf16_f32 v249, v4, v5
	v_cvt_pk_bf16_f32 v7, v14, v15
	v_lshlrev_b32_e32 v0, 16, v156
	v_and_b32_e32 v1, 0xffff0000, v156
	v_lshlrev_b32_e32 v2, 16, v164
	v_and_b32_e32 v3, 0xffff0000, v164
	v_pk_mul_f32 v[0:1], v[12:13], v[0:1] op_sel_hi:[0,1]
	v_pk_mul_f32 v[2:3], v[12:13], v[2:3] op_sel_hi:[0,1]
	v_pk_mul_f32 v[0:1], v[0:1], v[198:199]
	v_pk_mul_f32 v[2:3], v[2:3], v[244:245]
	v_pk_mul_f32 v[4:5], v[42:43], v[2:3]
	v_pk_mul_f32 v[14:15], v[44:45], v[2:3]
	v_pk_fma_f32 v[4:5], v[44:45], v[0:1], v[4:5]
	v_pk_fma_f32 v[14:15], v[42:43], v[0:1], v[14:15] neg_lo:[0,0,1] neg_hi:[0,0,1]
	s_nop 0
	v_cvt_pk_bf16_f32 v250, v4, v5
	v_cvt_pk_bf16_f32 v8, v14, v15
	v_lshlrev_b32_e32 v0, 16, v157
	v_and_b32_e32 v1, 0xffff0000, v157
	v_lshlrev_b32_e32 v2, 16, v165
	v_and_b32_e32 v3, 0xffff0000, v165
	v_pk_mul_f32 v[0:1], v[12:13], v[0:1] op_sel_hi:[0,1]
	v_pk_mul_f32 v[2:3], v[12:13], v[2:3] op_sel_hi:[0,1]
	v_pk_mul_f32 v[0:1], v[0:1], v[200:201]
	v_pk_mul_f32 v[2:3], v[2:3], v[246:247]
	v_pk_mul_f32 v[4:5], v[46:47], v[2:3]
	v_pk_mul_f32 v[14:15], v[48:49], v[2:3]
	v_pk_fma_f32 v[4:5], v[48:49], v[0:1], v[4:5]
	v_pk_fma_f32 v[14:15], v[46:47], v[0:1], v[14:15] neg_lo:[0,0,1] neg_hi:[0,0,1]
	s_nop 0
	v_cvt_pk_bf16_f32 v251, v4, v5
	v_cvt_pk_bf16_f32 v9, v14, v15
	global_store_dwordx4 v[10:11], v[6:9], off offset:144
	global_store_dwordx4 v[10:11], v[248:251], off offset:176
	s_cbranch_vccz .LBB0_198
	s_lshl_b32 s3, s9, 9
	s_lshl_b32 s2, s8, 20
	s_and_b32 s3, s3, 0xf8000
	s_or_b32 s96, s2, s3
	s_lshr_b32 s4, s9, 6
	s_lshl_b64 s[2:3], s[96:97], 1
	v_readlane_b32 s5, v255, 20
	s_add_u32 s2, s5, s2
	v_readlane_b32 s5, v255, 21
	s_addc_u32 s3, s5, s3
	s_mov_b32 s5, 0
	s_barrier
; DI int TID() { int t = threadIdx.x; asm volatile("" : "+v"(t)); return t; }
; DI void tr_load(const bfu* __restrict__ src, int pitch, bfu* T) {
;   const int tid = TID();
; #pragma unroll
;   for (int j = 0; j < 4; ++j) {
;     int c = tid + 256 * j; int tok = c >> 4, q = c & 15;
;     u32x2 v = *(const u32x2*)(src + (size_t)tok * pitch + q * 4);
;     *(unsigned*)(T + tok * TP + q * 4) = v[0];
;     *(unsigned*)(T + tok * TP + q * 4 + 2) = v[1];
;   }
; }
; DI void mlaprep_item(const Params& p, int L, int item, char* smem) {
;     ...
;   bfu* T = (bfu*)smem;
;   __syncthreads();
; #pragma unroll 1
;   for (int q = 0; q < 4; ++q) tr_load(p.kvraw + ((size_t)b * S + s0) * 512 + q * 128 + 64, 512, T + q * 64 * TP);
;   __syncthreads();
.LBB0_200:
	v_ashrrev_i32_e32 v0, 4, v224
	v_lshlrev_b32_e32 v1, 3, v224
	v_and_b32_e32 v5, 0x78, v1
	v_lshlrev_b32_e32 v2, 10, v0
	v_or_b32_e32 v2, v2, v5
	v_mov_b32_e32 v3, 0
	v_lshl_add_u64 v[2:3], s[2:3], 0, v[2:3]
	v_mul_lo_u32 v0, v0, s13
	v_add_u32_e32 v12, v0, v5
	s_lshl_b32 s98, s13, 4
	v_add_u32_e32 v13, s98, v12
	v_add_u32_e32 v14, s98, v13
	v_add_u32_e32 v15, s98, v14
	v_add_co_u32_e32 v6, vcc, 0x4000, v2
	v_addc_co_u32_e32 v7, vcc, 0, v3, vcc
	v_add_co_u32_e32 v8, vcc, 0x4000, v6
	v_addc_co_u32_e32 v9, vcc, 0, v7, vcc
	v_add_co_u32_e32 v10, vcc, 0x4000, v8
	v_addc_co_u32_e32 v11, vcc, 0, v9, vcc
	global_load_dwordx2 v[20:21], v[2:3], off
	global_load_dwordx2 v[22:23], v[6:7], off
	global_load_dwordx2 v[24:25], v[8:9], off
	global_load_dwordx2 v[26:27], v[10:11], off
	global_load_dwordx2 v[28:29], v[2:3], off offset:256
	global_load_dwordx2 v[30:31], v[6:7], off offset:256
	global_load_dwordx2 v[32:33], v[8:9], off offset:256
	global_load_dwordx2 v[34:35], v[10:11], off offset:256
	global_load_dwordx2 v[36:37], v[2:3], off offset:512
	global_load_dwordx2 v[38:39], v[6:7], off offset:512
	global_load_dwordx2 v[40:41], v[8:9], off offset:512
	global_load_dwordx2 v[42:43], v[10:11], off offset:512
	global_load_dwordx2 v[44:45], v[2:3], off offset:768
	global_load_dwordx2 v[46:47], v[6:7], off offset:768
	global_load_dwordx2 v[48:49], v[8:9], off offset:768
	global_load_dwordx2 v[50:51], v[10:11], off offset:768
	s_waitcnt vmcnt(15)
	ds_write2_b32 v12, v20, v21 offset1:1
	s_waitcnt vmcnt(14)
	ds_write2_b32 v13, v22, v23 offset1:1
	s_waitcnt vmcnt(13)
	ds_write2_b32 v14, v24, v25 offset1:1
	s_waitcnt vmcnt(12)
	ds_write2_b32 v15, v26, v27 offset1:1
	s_waitcnt vmcnt(11)
	v_add_u32_e32 v1, 0x2100, v12
	ds_write2_b32 v1, v28, v29 offset1:1
	s_waitcnt vmcnt(10)
	v_add_u32_e32 v1, 0x2100, v13
	ds_write2_b32 v1, v30, v31 offset1:1
	s_waitcnt vmcnt(9)
	v_add_u32_e32 v1, 0x2100, v14
	ds_write2_b32 v1, v32, v33 offset1:1
	s_waitcnt vmcnt(8)
	v_add_u32_e32 v1, 0x2100, v15
	ds_write2_b32 v1, v34, v35 offset1:1
	s_waitcnt vmcnt(7)
	v_add_u32_e32 v1, 0x4200, v12
	ds_write2_b32 v1, v36, v37 offset1:1
	s_waitcnt vmcnt(6)
	v_add_u32_e32 v1, 0x4200, v13
	ds_write2_b32 v1, v38, v39 offset1:1
	s_waitcnt vmcnt(5)
	v_add_u32_e32 v1, 0x4200, v14
	ds_write2_b32 v1, v40, v41 offset1:1
	s_waitcnt vmcnt(4)
	v_add_u32_e32 v1, 0x4200, v15
	ds_write2_b32 v1, v42, v43 offset1:1
	s_waitcnt vmcnt(3)
	v_add_u32_e32 v1, 0x6300, v12
	ds_write2_b32 v1, v44, v45 offset1:1
	s_waitcnt vmcnt(2)
	v_add_u32_e32 v1, 0x6300, v13
	ds_write2_b32 v1, v46, v47 offset1:1
	s_waitcnt vmcnt(1)
	v_add_u32_e32 v1, 0x6300, v14
	ds_write2_b32 v1, v48, v49 offset1:1
	s_waitcnt vmcnt(0)
	v_add_u32_e32 v1, 0x6300, v15
	ds_write2_b32 v1, v50, v51 offset1:1
	s_lshl_b32 s96, s8, 19
	s_and_b32 s2, s4, 31
	s_lshl_b32 s4, s2, 7
	s_lshl_b64 s[2:3], s[96:97], 1
	s_or_b32 s2, s2, s4
	v_readlane_b32 s4, v255, 14
	v_readlane_b32 s6, v255, 16
	v_readlane_b32 s7, v255, 17
	s_add_u32 s2, s6, s2
	s_addc_u32 s3, s7, s3
	s_mov_b32 s4, 0
	s_mov_b64 s[52:53], s[14:15]
	s_waitcnt lgkmcnt(0)
	s_barrier
	v_readlane_b32 s5, v255, 15
